# phase 4 only: attention workgroups run at s_setprio 3, their CU partner at 0; static slot-based setting restored at every grid barrier
# speedup vs baseline: 1.0005x; 1.0005x over previous
.LBB0_8:
	s_cmp_le_i32 s17, s6
	s_cbranch_scc1 .LBB0_62
	s_setprio 0
	v_readlane_b32 s4, v255, 49
	s_cmp_eq_u32 s4, -1
	s_cbranch_scc1 .Lprio_static
	s_bitcmp1_b32 s4, 8
	s_cbranch_scc0 .Lprio_static
	s_setprio 1
.Lprio_static:
	s_waitcnt vmcnt(0)
	s_barrier
	s_mov_b64 s[0:1], exec
	v_readlane_b32 s4, v252, 0
	v_readlane_b32 s5, v252, 1
	s_and_b64 s[4:5], s[0:1], s[4:5]
	s_mov_b64 exec, s[4:5]
	s_cbranch_execz .LBB0_61
	v_readlane_b32 s4, v254, 4
	s_waitcnt vmcnt(0) expcnt(0) lgkmcnt(0)
	s_nop 0
	v_mov_b32_e32 v2, s4
	ds_read_b32 v4, v2
	v_readlane_b32 s4, v254, 5
	s_waitcnt lgkmcnt(0)
	v_cmp_ne_u32_e32 vcc, 0, v4
	v_mov_b32_e32 v2, s4
	ds_read_b32 v2, v2
	s_cbranch_vccnz .LBB0_25
	v_readlane_b32 s6, v252, 2
	v_readlane_b32 s7, v252, 3
	s_load_dwordx2 s[4:5], s[6:7], 0x0
	s_nop 0
	s_load_dword s6, s[6:7], 0x8
	s_mov_b32 s16, 1
	s_waitcnt lgkmcnt(0)
	s_mul_i32 s13, s5, s4
	s_mul_i32 s13, s13, s6
	s_branch .LBB0_13

.LBB0_167:
	s_andn2_b64 vcc, exec, s[0:1]
	s_cbranch_vccnz .LBB0_308
	s_mov_b32 s13, s2
	s_setprio 0
	s_cmp_lt_u32 s2, 64
	s_cbranch_scc1 .Lp4_prio_done
	s_cmp_lt_u32 s2, 0x140
	s_cbranch_scc0 .Lp4_prio_done
	s_setprio 3
.Lp4_prio_done:
	s_cmpk_gt_i32 s13, 0x33f
	s_cbranch_scc1 .LBB0_231
	s_lshl_b32 s16, s24, 1
	s_branch .LBB0_171
